# MLP-up phase rstd table: 16 ssq-partial loads per thread in flight together instead of four serialized groups (same summation tree); on top of v65
# speedup vs baseline: 1.0018x; 1.0018x over previous
; __device__ __forceinline__ int opaque_tid() { int t = threadIdx.x; asm volatile("" : "+v"(t)); return t; }
; #define LAS __attribute__((address_space(3)))
; __device__ __forceinline__ float ssq_row(const float* part, int row) {
;     const f32x4* p = (const f32x4*)(part + (size_t)row * 16);
;     const f32x4 a = p[0], b = p[1], c = p[2], d = p[3];
;     return (((a[0] + a[1]) + (a[2] + a[3])) + ((b[0] + b[1]) + (b[2] + b[3]))) + (((c[0] + c[1]) + (c[2] + c[3])) + ((d[0] + d[1]) + (d[2] + d[3])));
; }
; template <class Sched> __device__ __forceinline__ bool build_rstd_table(LAS unsigned char* lds, const Sched& S, const float* ssq) {
;     const int tid = opaque_tid(), i = tid >> 6, r0 = tid & 63;
;     pg8::Unit uu;
;     if (S.next(8, uu)) return false;
;     LAS float* tab = (LAS float*)(lds + pg8::RSTD_TAB);
;     if (S.next(i, uu)) {
; #pragma unroll
;         for (int k = 0; k < 4; ++k) tab[i * 256 + r0 + 64 * k] = __builtin_amdgcn_rsqf(pg8::ssq_row(ssq, uu.pm * 256 + r0 + 64 * k) * (1.0f / 1024.0f) + EPS);
;     }
.LBB0_1730:
	s_andn2_b64 vcc, exec, s[0:1]
	s_cbranch_vccnz .LBB0_1829
	v_readlane_b32 s0, v254, 62
	v_readlane_b32 s1, v254, 63
	s_waitcnt vmcnt(0)
	v_mov_b32_e32 v3, v210
	s_andn2_b64 vcc, exec, s[0:1]
	v_cndmask_b32_e64 v0, 0, 1, s[0:1]
	v_cmp_ne_u32_e64 s[40:41], 1, v0
	s_cbranch_vccnz .LBB0_1739
	v_ashrrev_i32_e32 v2, 6, v3
	s_waitcnt lgkmcnt(0)
	v_mov_b64_e32 v[0:1], s[2:3]
	v_mad_i64_i32 v[0:1], s[0:1], v2, s28, v[0:1]
	s_mov_b64 s[0:1], 0x800
	s_nop 0
	v_cmp_gt_i64_e32 vcc, s[0:1], v[0:1]
	s_and_saveexec_b64 s[0:1], vcc
	s_cbranch_execz .LBB0_1738
	v_ashrrev_i32_e32 v1, 31, v0
	v_lshrrev_b32_e32 v1, 29, v1
	v_add_u32_e32 v1, v0, v1
	v_and_b32_e32 v4, -8, v1
	v_sub_u32_e32 v4, v0, v4
	v_cmp_lt_i32_e32 vcc, -1, v4
	s_and_saveexec_b64 s[8:9], vcc
	s_xor_b64 s[38:39], exec, s[8:9]
	v_lshlrev_b32_e32 v0, 8, v4
	s_andn2_saveexec_b64 s[38:39], s[38:39]
	v_lshl_add_u32 v0, v4, 8, v4
	s_or_b64 exec, exec, s[38:39]
	v_ashrrev_i32_e32 v1, 3, v1
	v_add_u32_e32 v0, v0, v1
	v_ashrrev_i32_e32 v1, 31, v0
	v_lshrrev_b32_e32 v1, 25, v1
	v_add_u32_e32 v1, v0, v1
	v_ashrrev_i32_e32 v4, 7, v1
	v_lshlrev_b32_e32 v4, 3, v4
	v_and_b32_e32 v1, 0xffffff80, v1
	v_sub_u32_e32 v5, 0x80, v4
	v_sub_u32_e32 v0, v0, v1
	v_min_i32_e32 v5, 8, v5
	v_sub_u32_e32 v6, 0, v0
	v_ashrrev_i32_e32 v1, 31, v0
	v_max_i32_e32 v0, v0, v6
	v_sub_u32_e32 v6, 0, v5
	v_max_i32_e32 v5, v5, v6
	v_cvt_f32_u32_e32 v6, v5
	v_sub_u32_e32 v7, 0, v5
	v_and_b32_e32 v3, 63, v3
	v_readlane_b32 s8, v254, 55
	v_rcp_iflag_f32_e32 v6, v6
	s_nop 0
	v_mul_f32_e32 v6, 0x4f7ffffe, v6
	v_cvt_u32_f32_e32 v6, v6
	v_mul_lo_u32 v7, v7, v6
	v_mul_hi_u32 v7, v6, v7
	v_add_u32_e32 v6, v6, v7
	v_mul_hi_u32 v6, v0, v6
	v_mul_lo_u32 v6, v6, v5
	v_sub_u32_e32 v0, v0, v6
	v_cmp_ge_u32_e32 vcc, v0, v5
	v_sub_u32_e32 v6, v0, v5
	s_nop 0
	v_cndmask_b32_e32 v0, v0, v6, vcc
	v_cmp_ge_u32_e32 vcc, v0, v5
	v_sub_u32_e32 v5, v0, v5
	s_nop 0
	v_cndmask_b32_e32 v0, v0, v5, vcc
	v_xor_b32_e32 v0, v0, v1
	v_sub_u32_e32 v0, v0, v1
	v_add_u32_e32 v0, v4, v0
	v_lshl_or_b32 v0, v0, 8, v3
	v_lshlrev_b32_e32 v1, 10, v2
	v_lshlrev_b32_e32 v2, 2, v3
	v_add3_u32 v8, s8, v1, v2
	v_ashrrev_i32_e32 v1, 31, v0
	v_lshlrev_b64 v[2:3], 6, v[0:1]
	v_lshl_add_u64 v[6:7], s[6:7], 0, v[2:3]
	v_or_b32_e32 v22, 64, v0
	v_ashrrev_i32_e32 v23, 31, v22
	v_lshlrev_b64 v[22:23], 6, v[22:23]
	v_lshl_add_u64 v[22:23], s[6:7], 0, v[22:23]
	v_or_b32_e32 v24, 0x80, v0
	v_ashrrev_i32_e32 v25, 31, v24
	v_lshlrev_b64 v[24:25], 6, v[24:25]
	v_lshl_add_u64 v[24:25], s[6:7], 0, v[24:25]
	v_or_b32_e32 v26, 0xc0, v0
	v_ashrrev_i32_e32 v27, 31, v26
	v_lshlrev_b64 v[26:27], 6, v[26:27]
	v_lshl_add_u64 v[26:27], s[6:7], 0, v[26:27]
	global_load_dwordx4 v[28:31], v[6:7], off
	global_load_dwordx4 v[32:35], v[6:7], off offset:16
	global_load_dwordx4 v[36:39], v[6:7], off offset:32
	global_load_dwordx4 v[40:43], v[6:7], off offset:48
	global_load_dwordx4 v[44:47], v[22:23], off
	global_load_dwordx4 v[48:51], v[22:23], off offset:16
	global_load_dwordx4 v[52:55], v[22:23], off offset:32
	global_load_dwordx4 v[56:59], v[22:23], off offset:48
	global_load_dwordx4 v[60:63], v[24:25], off
	global_load_dwordx4 v[64:67], v[24:25], off offset:16
	global_load_dwordx4 v[68:71], v[24:25], off offset:32
	global_load_dwordx4 v[72:75], v[24:25], off offset:48
	global_load_dwordx4 v[76:79], v[26:27], off
	global_load_dwordx4 v[80:83], v[26:27], off offset:16
	global_load_dwordx4 v[84:87], v[26:27], off offset:32
	global_load_dwordx4 v[88:91], v[26:27], off offset:48
	s_waitcnt vmcnt(12)
	v_add_f32_e32 v10, v28, v29
	v_add_f32_e32 v11, v30, v31
	v_add_f32_e32 v10, v10, v11
	v_add_f32_e32 v11, v32, v33
	v_add_f32_e32 v12, v34, v35
	v_add_f32_e32 v11, v11, v12
	v_add_f32_e32 v10, v10, v11
	v_add_f32_e32 v11, v36, v37
	v_add_f32_e32 v12, v38, v39
	v_add_f32_e32 v11, v11, v12
	v_add_f32_e32 v12, v40, v41
	v_add_f32_e32 v13, v42, v43
	v_add_f32_e32 v12, v12, v13
	v_add_f32_e32 v11, v11, v12
	v_add_f32_e32 v1, v10, v11
	v_fmamk_f32 v1, v1, 0x3a800000, v211
	v_rsq_f32_e32 v1, v1
	s_waitcnt vmcnt(8)
	v_add_f32_e32 v10, v44, v45
	v_add_f32_e32 v11, v46, v47
	v_add_f32_e32 v10, v10, v11
	v_add_f32_e32 v11, v48, v49
	v_add_f32_e32 v12, v50, v51
	v_add_f32_e32 v11, v11, v12
	v_add_f32_e32 v10, v10, v11
	v_add_f32_e32 v11, v52, v53
	v_add_f32_e32 v12, v54, v55
	v_add_f32_e32 v11, v11, v12
	v_add_f32_e32 v12, v56, v57
	v_add_f32_e32 v13, v58, v59
	v_add_f32_e32 v12, v12, v13
	v_add_f32_e32 v11, v11, v12
	v_add_f32_e32 v2, v10, v11
	v_fmamk_f32 v2, v2, 0x3a800000, v211
	v_rsq_f32_e32 v2, v2
	s_waitcnt vmcnt(4)
	v_add_f32_e32 v10, v60, v61
	v_add_f32_e32 v11, v62, v63
	v_add_f32_e32 v10, v10, v11
	v_add_f32_e32 v11, v64, v65
	v_add_f32_e32 v12, v66, v67
	v_add_f32_e32 v11, v11, v12
	v_add_f32_e32 v10, v10, v11
	v_add_f32_e32 v11, v68, v69
	v_add_f32_e32 v12, v70, v71
	v_add_f32_e32 v11, v11, v12
	v_add_f32_e32 v12, v72, v73
	v_add_f32_e32 v13, v74, v75
	v_add_f32_e32 v12, v12, v13
	v_add_f32_e32 v11, v11, v12
	v_add_f32_e32 v9, v10, v11
	v_fmamk_f32 v9, v9, 0x3a800000, v211
	v_rsq_f32_e32 v9, v9
	s_waitcnt vmcnt(0)
	v_add_f32_e32 v10, v76, v77
	v_add_f32_e32 v11, v78, v79
	v_add_f32_e32 v10, v10, v11
	v_add_f32_e32 v11, v80, v81
	v_add_f32_e32 v12, v82, v83
	v_add_f32_e32 v11, v11, v12
	v_add_f32_e32 v10, v10, v11
	v_add_f32_e32 v11, v84, v85
	v_add_f32_e32 v12, v86, v87
	v_add_f32_e32 v11, v11, v12
	v_add_f32_e32 v12, v88, v89
	v_add_f32_e32 v13, v90, v91
	v_add_f32_e32 v12, v12, v13
	v_add_f32_e32 v11, v11, v12
	v_add_f32_e32 v3, v10, v11
	v_fmamk_f32 v3, v3, 0x3a800000, v211
	v_rsq_f32_e32 v3, v3
	ds_write2st64_b32 v8, v1, v2 offset1:1
	ds_write2st64_b32 v8, v9, v3 offset0:2 offset1:3
